# counted per-MFMA LDS waits in the stick-breaking QK step; MLA loop head no longer recomputes buffer offsets; on top of the MLA back-edge rotation
# speedup vs baseline: 1.0108x; 1.0059x over previous
; template <bool DRY> __device__ __forceinline__ void sb_unit(int b, int h, int qi, bf16_t* Pm, const bf16_t* VT) {
;     ...
;         sb_load(nxt, Pm, VT, tok0, (kt > 0 ? kt - 1 : 0) * 32, h, r32, hi);
;         f32x16 p = {};
; #pragma unroll
;         for (int s = 0; s < 4; ++s) p = __builtin_amdgcn_mfma_f32_32x32x16_bf16(cur.kf[s], qf[s], p, 0, 0, 0);
.Lsb_nostep_a:
.LBB0_742:
	s_xor_b32 s98, s98, 0x2000
	s_xor_b32 s99, s98, 0x2000
	v_add_u32_e32 v210, s99, v192
	v_add_u32_e32 v211, s99, v193
	v_add_u32_e32 v212, s99, v194
	v_add_u32_e32 v213, s99, v195
	v_add_u32_e32 v214, s99, v196
	v_add_u32_e32 v215, s99, v197
	v_add_u32_e32 v216, s99, v198
	v_add_u32_e32 v217, s99, v199
	s_waitcnt vmcnt(0)
	ds_read_b128 v[136:139], v210
	ds_read_b128 v[112:115], v211
	ds_read_b128 v[108:111], v212
	ds_read_b128 v[104:107], v213
	ds_read_b64 v[80:81], v214 offset:4096
	ds_read_b64 v[82:83], v215 offset:4096
	ds_read_b64 v[72:73], v216 offset:4096
	ds_read_b64 v[74:75], v217 offset:4096
	ds_read_b64 v[76:77], v214 offset:6144
	ds_read_b64 v[78:79], v215 offset:6144
	ds_read_b64 v[68:69], v216 offset:6144
	ds_read_b64 v[70:71], v217 offset:6144
	s_waitcnt lgkmcnt(11)
	v_mfma_f32_32x32x16_bf16 v[36:51], v[136:139], v[52:55], 0
	s_waitcnt lgkmcnt(10)
	v_mfma_f32_32x32x16_bf16 v[36:51], v[112:115], v[56:59], v[36:51]
	s_waitcnt lgkmcnt(9)
	v_mfma_f32_32x32x16_bf16 v[36:51], v[108:111], v[60:63], v[36:51]
	s_waitcnt lgkmcnt(8)
	v_mfma_f32_32x32x16_bf16 v[36:51], v[104:107], v[64:67], v[36:51]
	s_add_i32 m0, s98, 0
	s_nop 0
	global_load_lds_dwordx4 v[172:173], off
	s_add_i32 m0, s98, 1024
	s_nop 0
	global_load_lds_dwordx4 v[174:175], off
	s_add_i32 m0, s98, 2048
	s_nop 0
	global_load_lds_dwordx4 v[176:177], off
	s_add_i32 m0, s98, 3072
	s_nop 0
	global_load_lds_dwordx4 v[178:179], off
	s_add_i32 m0, s98, 4096
	s_nop 0
	global_load_lds_dwordx4 v[180:181], off
	s_add_i32 m0, s98, 5120
	s_nop 0
	global_load_lds_dwordx4 v[182:183], off
	s_add_i32 m0, s98, 6144
	s_nop 0
	global_load_lds_dwordx4 v[184:185], off
	s_add_i32 m0, s98, 7168
	s_nop 0
	global_load_lds_dwordx4 v[186:187], off
	v_cmp_lt_i32_e32 vcc, 0, v100
	v_add_u32_e32 v100, -1, v100
	s_nop 0
	s_cbranch_vccz .Lsb_nostep_b
	v_lshl_add_u64 v[172:173], v[172:173], 0, v[188:189]
	v_lshl_add_u64 v[174:175], v[174:175], 0, v[188:189]
	v_lshl_add_u64 v[176:177], v[176:177], 0, v[188:189]
	v_lshl_add_u64 v[178:179], v[178:179], 0, v[188:189]
	v_lshl_add_u64 v[180:181], v[180:181], 0, v[190:191]
	v_lshl_add_u64 v[182:183], v[182:183], 0, v[190:191]
	v_lshl_add_u64 v[184:185], v[184:185], 0, v[190:191]
	v_lshl_add_u64 v[186:187], v[186:187], 0, v[190:191]

; template <bool DRY> __device__ __forceinline__ void sb_unit(int b, int h, int qi, bf16_t* Pm, const bf16_t* VT) {
;     ...
;         sb_load(nxt, Pm, VT, tok0, (kt > 0 ? kt - 1 : 0) * 32, h, r32, hi);
;         f32x16 p = {};
; #pragma unroll
;         for (int s = 0; s < 4; ++s) p = __builtin_amdgcn_mfma_f32_32x32x16_bf16(cur.kf[s], qf[s], p, 0, 0, 0);
.Lsbl_loop:
	s_xor_b32 s98, s98, 0x2000
	s_xor_b32 s99, s98, 0x2000
	v_add_u32_e32 v210, s99, v192
	v_add_u32_e32 v211, s99, v193
	v_add_u32_e32 v212, s99, v194
	v_add_u32_e32 v213, s99, v195
	v_add_u32_e32 v214, s99, v196
	v_add_u32_e32 v215, s99, v197
	v_add_u32_e32 v216, s99, v198
	v_add_u32_e32 v217, s99, v199
	s_waitcnt vmcnt(0)
	ds_read_b128 v[136:139], v210
	ds_read_b128 v[112:115], v211
	ds_read_b128 v[108:111], v212
	ds_read_b128 v[104:107], v213
	ds_read_b64 v[80:81], v214 offset:4096
	ds_read_b64 v[82:83], v215 offset:4096
	ds_read_b64 v[72:73], v216 offset:4096
	ds_read_b64 v[74:75], v217 offset:4096
	ds_read_b64 v[76:77], v214 offset:6144
	ds_read_b64 v[78:79], v215 offset:6144
	ds_read_b64 v[68:69], v216 offset:6144
	ds_read_b64 v[70:71], v217 offset:6144
	s_waitcnt lgkmcnt(11)
	v_mfma_f32_32x32x16_bf16 v[36:51], v[136:139], v[52:55], 0
	s_waitcnt lgkmcnt(10)
	v_mfma_f32_32x32x16_bf16 v[36:51], v[112:115], v[56:59], v[36:51]
	s_waitcnt lgkmcnt(9)
	v_mfma_f32_32x32x16_bf16 v[36:51], v[108:111], v[60:63], v[36:51]
	s_waitcnt lgkmcnt(8)
	v_mfma_f32_32x32x16_bf16 v[36:51], v[104:107], v[64:67], v[36:51]
	s_add_i32 m0, s98, 0
	s_nop 0
	global_load_lds_dwordx4 v[172:173], off
	s_add_i32 m0, s98, 1024
	s_nop 0
	global_load_lds_dwordx4 v[174:175], off
	s_add_i32 m0, s98, 2048
	s_nop 0
	global_load_lds_dwordx4 v[176:177], off
	s_add_i32 m0, s98, 3072
	s_nop 0
	global_load_lds_dwordx4 v[178:179], off
	s_add_i32 m0, s98, 4096
	s_nop 0
	global_load_lds_dwordx4 v[180:181], off
	s_add_i32 m0, s98, 5120
	s_nop 0
	global_load_lds_dwordx4 v[182:183], off
	s_add_i32 m0, s98, 6144
	s_nop 0
	global_load_lds_dwordx4 v[184:185], off
	s_add_i32 m0, s98, 7168
	s_nop 0
	global_load_lds_dwordx4 v[186:187], off
	v_cmp_lt_i32_e32 vcc, 0, v100
	v_add_u32_e32 v100, -1, v100
	s_nop 0
	s_cbranch_vccz .Lsb_nostep_c
	v_lshl_add_u64 v[172:173], v[172:173], 0, v[188:189]
	v_lshl_add_u64 v[174:175], v[174:175], 0, v[188:189]
	v_lshl_add_u64 v[176:177], v[176:177], 0, v[188:189]
	v_lshl_add_u64 v[178:179], v[178:179], 0, v[188:189]
	v_lshl_add_u64 v[180:181], v[180:181], 0, v[190:191]
	v_lshl_add_u64 v[182:183], v[182:183], 0, v[190:191]
	v_lshl_add_u64 v[184:185], v[184:185], 0, v[190:191]
	v_lshl_add_u64 v[186:187], v[186:187], 0, v[190:191]

; #define LAS __attribute__((address_space(3)))
; #define LDS_BARRIER() do { asm volatile("s_waitcnt lgkmcnt(0)" ::: "memory"); __builtin_amdgcn_s_barrier(); asm volatile("" ::: "memory"); } while (0)
; template <bool DRY> __device__ __forceinline__ void mla_unit(LAS unsigned char* lds, int b, int h, int qb, const bf16_t* Q, const bf16_t* Kn, const bf16_t* Pm, const bf16_t* VT, bf16_t* Y) {
;     ...
;         LAS unsigned char* kbuf = lds + (t & 1) * MLA_KB; LAS unsigned char* vbuf = lds + 2 * MLA_KB + (t & 1) * MLA_VB;
;         *(LAS u32x4*)(kbuf + ka_dst) = ra; if (tid < 256) *(LAS u32x4*)(kbuf + kb_dst) = rb; *(LAS u32x4*)(vbuf + va_dst) = rv;
;         LDS_BARRIER();
;         if (t + 1 < NT) { ra = *(const u32x4*)(ka_src + (size_t)(t + 1) * 64 * 512); rb = *(const u32x4*)(kb_src + (size_t)(t + 1) * 64 * PW); rv = *(const u32x4*)(va_src + (t + 1) * 64); }
.LBB0_802:
	s_waitcnt lgkmcnt(0)
	s_add_i32 s22, s57, 1
	s_cmp_ge_u32 s22, s41
	s_cbranch_scc1 .Lmla_nl
	v_lshl_add_u64 v[0:1], s[28:29], 1, v[114:115]
	global_load_dwordx4 v[100:103], v[118:119], off
	global_load_dwordx4 v[96:99], v[116:117], off
	global_load_dwordx4 v[88:91], v[0:1], off
